# Up side-GEMM k-loop: coalesced loads (lane=row*4+chunk) + ds_bpermute to MFMA layout, all k-steps prefetched
# speedup vs baseline: 1.0017x; 1.0017x over previous
.LBB0_2260:
	s_or_b64 exec, exec, s[4:5]
	v_readlane_b32 s83, v255, 9
	v_readlane_b32 s4, v255, 8
	s_load_dwordx4 s[0:3], s[96:97], 0xe8
	v_readlane_b32 s84, v255, 0
	s_waitcnt lgkmcnt(0)
	s_barrier
	s_add_u32 s22, s2, 0xe1cb000
	s_addc_u32 s23, s3, 0
	s_lshl_b32 s0, s28, 23
	s_add_u32 s0, s2, s0
	s_addc_u32 s1, s3, 0
	s_add_u32 s24, s0, 0x1500000
	s_addc_u32 s25, s1, 0
	s_lshl_b32 s82, s28, 1
	s_or_b32 s54, s82, 1
	s_lshl_b64 s[0:1], s[54:55], 21
	s_add_u32 s0, s2, s0
	s_addc_u32 s1, s3, s1
	s_add_u32 s26, s0, 0x5e7f3000
	s_addc_u32 s27, s1, 0
	s_lshl_b64 s[0:1], s[54:55], 16
	s_add_u32 s0, s2, s0
	s_addc_u32 s1, s3, s1
	s_add_u32 s34, s0, 0x5fff3000
	s_addc_u32 s35, s1, 0
	s_add_u32 s44, s2, 0x366cb000
	s_addc_u32 s45, s3, 0
	s_ashr_i32 s54, s83, 31
	s_lshr_b32 s1, s54, 24
	s_lshl_b32 s50, s4, 6
	s_add_i32 s1, s83, s1
	v_mbcnt_lo_u32_b32 v4, -1, 0
	v_mbcnt_hi_u32_b32 v4, -1, v4
	s_ashr_i32 s1, s1, 8
	v_add_u32_e32 v0, s50, v4
	s_nop 0
	v_readfirstlane_b32 s0, v0
	v_med3_i32 v0, s1, 1, 9
	s_nop 0
	v_readfirstlane_b32 s51, v0
	s_lshl_b32 s62, s51, 8
	s_cmp_ge_i32 s84, s62
	s_cbranch_scc1 .LBB0_2329
	v_and_b32_e32 v3, 15, v4
	v_cvt_f32_u32_e32 v10, s51
	v_lshlrev_b32_e32 v8, 11, v3
	v_mov_b32_e32 v9, v2
	v_and_b32_e32 v6, 48, v4
	v_mov_b32_e32 v7, v2
	v_lshl_add_u64 v[8:9], s[22:23], 0, v[8:9]
	s_ashr_i32 s85, s0, 6
	v_lshl_add_u64 v[0:1], s[24:25], 0, v[6:7]
	v_lshl_add_u64 v[6:7], v[8:9], 0, v[6:7]
	s_mov_b64 s[0:1], 0x4000000
	s_waitcnt vmcnt(9)
	v_lshl_add_u64 v[80:81], v[6:7], 0, s[0:1]
	v_lshrrev_b32_e32 v229, 2, v4
	v_and_b32_e32 v234, 3, v4
	v_lshlrev_b32_e32 v234, 4, v234
	v_mov_b32_e32 v235, 0
	v_lshl_add_u64 v[230:231], s[24:25], 0, v[234:235]
	v_lshlrev_b32_e32 v236, 11, v229
	v_mov_b32_e32 v237, 0
	v_lshl_add_u64 v[232:233], s[22:23], 0, v[236:237]
	v_lshl_add_u64 v[232:233], v[232:233], 0, v[234:235]
	v_lshl_add_u64 v[232:233], v[232:233], 0, s[0:1]
	v_lshrrev_b32_e32 v228, 4, v4
	v_lshlrev_b32_e32 v228, 2, v228
	v_lshl_add_u32 v228, v3, 4, v228
	v_rcp_iflag_f32_e32 v6, v10
	v_and_b32_e32 v5, 63, v4
	s_waitcnt vmcnt(0)
	v_lshl_add_u32 v86, v5, 4, 0
	s_cmp_lt_i32 s85, 32
	v_mul_f32_e32 v5, 0x4f7ffffe, v6
	v_cvt_u32_f32_e32 v5, v5
	s_cselect_b64 s[46:47], -1, 0
	s_sub_i32 s0, 0, s51
	v_lshrrev_b32_e32 v4, 2, v4
	v_readfirstlane_b32 s1, v5
	s_mul_i32 s0, s0, s1
	s_mul_hi_u32 s0, s1, s0
	v_and_b32_e32 v87, 12, v4
	s_add_i32 s86, s1, s0
	s_add_i32 s87, s85, -8
	s_lshl_b32 s88, s85, 5
	s_mov_b32 s89, s84
	s_branch .LBB0_2263

.LBB0_2263:
	s_abs_i32 s1, s89
	s_mul_hi_u32 s2, s1, s86
	s_mul_i32 s3, s2, s51
	s_sub_i32 s1, s1, s3
	s_ashr_i32 s0, s89, 31
	s_add_i32 s3, s2, 1
	s_sub_i32 s4, s1, s51
	s_cmp_ge_u32 s1, s51
	s_cselect_b32 s2, s3, s2
	s_cselect_b32 s1, s4, s1
	s_add_i32 s3, s2, 1
	s_cmp_ge_u32 s1, s51
	s_cselect_b32 s1, s3, s2
	s_xor_b32 s1, s1, s0
	s_sub_i32 s1, s1, s0
	s_mul_i32 s0, s1, s51
	s_sub_i32 s0, s89, s0
	s_mul_i32 s2, s0, 9
	s_abs_i32 s4, s2
	s_mul_hi_u32 s5, s4, s86
	s_mul_i32 s6, s5, s51
	s_sub_i32 s4, s4, s6
	s_add_i32 s3, s2, 9
	s_ashr_i32 s0, s2, 31
	s_add_i32 s6, s5, 1
	s_sub_i32 s7, s4, s51
	s_cmp_ge_u32 s4, s51
	s_cselect_b32 s5, s6, s5
	s_cselect_b32 s4, s7, s4
	s_add_i32 s6, s5, 1
	s_cmp_ge_u32 s4, s51
	s_cselect_b32 s4, s6, s5
	s_sub_i32 s2, -9, s2
	s_xor_b32 s4, s4, s0
	s_max_i32 s2, s3, s2
	s_sub_i32 s0, s4, s0
	s_ashr_i32 s4, s3, 31
	s_mul_hi_u32 s3, s2, s86
	s_mul_i32 s5, s3, s51
	s_sub_i32 s2, s2, s5
	s_add_i32 s5, s3, 1
	s_sub_i32 s6, s2, s51
	s_cmp_ge_u32 s2, s51
	s_cselect_b32 s3, s5, s3
	s_cselect_b32 s2, s6, s2
	s_add_i32 s5, s3, 1
	s_cmp_ge_u32 s2, s51
	s_cselect_b32 s2, s5, s3
	s_xor_b32 s2, s2, s4
	s_sub_i32 s90, s2, s4
	s_lshl_b32 s1, s1, 4
	s_andn2_b64 vcc, exec, s[46:47]
	v_mov_b32_e32 v75, 0
	s_cbranch_vccnz .LBB0_2302
	s_cmp_lt_i32 s0, 1
	s_cselect_b64 s[2:3], -1, 0
	s_cmp_gt_i32 s90, 0
	s_cselect_b64 s[4:5], -1, 0
	s_and_b64 s[28:29], s[2:3], s[4:5]
	s_cmp_lt_i32 s0, 2
	s_cselect_b64 s[2:3], -1, 0
	s_cmp_gt_i32 s90, 1
	s_cselect_b64 s[4:5], -1, 0
	s_and_b64 s[30:31], s[2:3], s[4:5]
	s_cmp_lt_i32 s0, 3
	s_cselect_b64 s[2:3], -1, 0
	s_cmp_gt_i32 s90, 2
	s_cselect_b64 s[4:5], -1, 0
	s_and_b64 s[52:53], s[2:3], s[4:5]
	s_cmp_lt_i32 s0, 4
	s_cselect_b64 s[2:3], -1, 0
	s_cmp_gt_i32 s90, 3
	s_cselect_b64 s[4:5], -1, 0
	s_and_b64 s[56:57], s[2:3], s[4:5]
	s_cmp_lt_i32 s0, 5
	s_cselect_b64 s[2:3], -1, 0
	s_cmp_gt_i32 s90, 4
	s_cselect_b64 s[4:5], -1, 0
	s_and_b64 s[66:67], s[2:3], s[4:5]
	s_cmp_lt_i32 s0, 6
	s_cselect_b64 s[2:3], -1, 0
	s_cmp_gt_i32 s90, 5
	s_cselect_b64 s[4:5], -1, 0
	s_and_b64 s[76:77], s[2:3], s[4:5]
	s_cmp_lt_i32 s0, 7
	s_cselect_b64 s[2:3], -1, 0
	s_cmp_gt_i32 s90, 6
	s_cselect_b64 s[4:5], -1, 0
	s_and_b64 s[78:79], s[2:3], s[4:5]
	s_cmp_lt_i32 s0, 8
	s_cselect_b64 s[2:3], -1, 0
	s_cmp_gt_i32 s90, 7
	s_cselect_b64 s[4:5], -1, 0
	v_or_b32_e32 v40, s1, v3
	v_or_b32_e32 v238, s1, v229
	v_mov_b32_e32 v239, 0
	v_lshlrev_b64 v[238:239], 11, v[238:239]
	v_lshl_add_u64 v[238:239], v[230:231], 0, v[238:239]
	s_and_b64 s[80:81], s[2:3], s[4:5]
	v_ashrrev_i32_e32 v41, 31, v40
	s_cmp_lt_i32 s0, 9
	v_lshlrev_b64 v[40:41], 11, v[40:41]
	s_cselect_b64 s[2:3], -1, 0
	s_cmp_gt_i32 s90, 8
	v_lshl_add_u64 v[82:83], v[0:1], 0, v[40:41]
	s_cselect_b64 s[4:5], -1, 0
	v_mov_b32_e32 v40, 0
	s_and_b64 s[70:71], s[2:3], s[4:5]
	s_mov_b32 s2, s88
	s_mov_b32 s91, s87
	v_mov_b32_e32 v41, v40
	v_mov_b32_e32 v42, v40
	v_mov_b32_e32 v43, v40
	v_mov_b32_e32 v44, v40
	v_mov_b32_e32 v45, v40
	v_mov_b32_e32 v46, v40
	v_mov_b32_e32 v47, v40
	v_mov_b32_e32 v48, v40
	v_mov_b32_e32 v49, v40
	v_mov_b32_e32 v50, v40
	v_mov_b32_e32 v51, v40
	v_mov_b32_e32 v52, v40
	v_mov_b32_e32 v53, v40
	v_mov_b32_e32 v54, v40
	v_mov_b32_e32 v55, v40
	v_mov_b32_e32 v56, v40
	v_mov_b32_e32 v57, v40
	v_mov_b32_e32 v58, v40
	v_mov_b32_e32 v59, v40
	v_mov_b32_e32 v60, v40
	v_mov_b32_e32 v61, v40
	v_mov_b32_e32 v62, v40
	v_mov_b32_e32 v63, v40
	v_mov_b32_e32 v64, v40
	v_mov_b32_e32 v65, v40
	v_mov_b32_e32 v66, v40
	v_mov_b32_e32 v67, v40
	v_mov_b32_e32 v68, v40
	v_mov_b32_e32 v69, v40
	v_mov_b32_e32 v70, v40
	v_mov_b32_e32 v71, v40
	v_mov_b32_e32 v72, v40
	v_mov_b32_e32 v73, v40
	v_mov_b32_e32 v74, v40
	v_mov_b32_e32 v75, v40
	s_branch .LBB0_2266
.LBB0_2266:
	s_lshl_b32 s4, s2, 1
	s_mov_b32 s5, 0
	s_mov_b64 s[6:7], 0x8000
	v_lshl_add_u64 v[240:241], v[238:239], 0, s[4:5]
	v_lshl_add_u64 v[242:243], v[232:233], 0, s[4:5]
	global_load_dwordx4 v[106:109], v[240:241], off
	global_load_dwordx4 v[110:113], v[240:241], off offset:512
	global_load_dwordx4 v[114:117], v[240:241], off offset:1024
	global_load_dwordx4 v[118:121], v[240:241], off offset:1536
	v_lshl_add_u64 v[244:245], v[242:243], 0, s[6:7]
	s_and_b64 vcc, exec, s[28:29]
	s_cbranch_vccz .Lsu_ld0
	global_load_dwordx4 v[122:125], v[242:243], off
	global_load_dwordx4 v[126:129], v[242:243], off offset:512
	global_load_dwordx4 v[130:133], v[242:243], off offset:1024
	global_load_dwordx4 v[134:137], v[242:243], off offset:1536
.Lsu_ld0:
	v_lshl_add_u64 v[242:243], v[244:245], 0, s[6:7]
	s_and_b64 vcc, exec, s[30:31]
	s_cbranch_vccz .Lsu_ld1
	global_load_dwordx4 v[138:141], v[244:245], off
	global_load_dwordx4 v[142:145], v[244:245], off offset:512
	global_load_dwordx4 v[146:149], v[244:245], off offset:1024
	global_load_dwordx4 v[150:153], v[244:245], off offset:1536
.Lsu_ld1:
	v_lshl_add_u64 v[244:245], v[242:243], 0, s[6:7]
	s_and_b64 vcc, exec, s[52:53]
	s_cbranch_vccz .Lsu_ld2
	global_load_dwordx4 v[154:157], v[242:243], off
	global_load_dwordx4 v[158:161], v[242:243], off offset:512
	global_load_dwordx4 v[162:165], v[242:243], off offset:1024
	global_load_dwordx4 v[166:169], v[242:243], off offset:1536
.Lsu_ld2:
	v_lshl_add_u64 v[242:243], v[244:245], 0, s[6:7]
	s_and_b64 vcc, exec, s[56:57]
	s_cbranch_vccz .Lsu_ld3
	global_load_dwordx4 v[170:173], v[244:245], off
	global_load_dwordx4 v[174:177], v[244:245], off offset:512
	global_load_dwordx4 v[178:181], v[244:245], off offset:1024
	global_load_dwordx4 v[182:185], v[244:245], off offset:1536
.Lsu_ld3:
	v_lshl_add_u64 v[244:245], v[242:243], 0, s[6:7]
	s_and_b64 vcc, exec, s[66:67]
	s_cbranch_vccz .Lsu_ld4
	global_load_dwordx4 v[186:189], v[242:243], off
	global_load_dwordx4 v[190:193], v[242:243], off offset:512
	global_load_dwordx4 v[194:197], v[242:243], off offset:1024
	global_load_dwordx4 v[198:201], v[242:243], off offset:1536
.Lsu_ld4:
	v_lshl_add_u64 v[242:243], v[244:245], 0, s[6:7]
	s_and_b64 vcc, exec, s[76:77]
	s_cbranch_vccz .Lsu_ld5
	global_load_dwordx4 v[202:205], v[244:245], off
	global_load_dwordx4 v[206:209], v[244:245], off offset:512
	global_load_dwordx4 v[210:213], v[244:245], off offset:1024
	global_load_dwordx4 v[214:217], v[244:245], off offset:1536
.Lsu_ld5:
	v_lshl_add_u64 v[244:245], v[242:243], 0, s[6:7]
	s_and_b64 vcc, exec, s[78:79]
	s_cbranch_vccz .Lsu_ld6
	global_load_dwordx4 v[218:221], v[242:243], off
	global_load_dwordx4 v[4:7], v[242:243], off offset:512
	global_load_dwordx4 v[8:11], v[242:243], off offset:1024
	global_load_dwordx4 v[12:15], v[242:243], off offset:1536
.Lsu_ld6:
	v_lshl_add_u64 v[242:243], v[244:245], 0, s[6:7]
	s_and_b64 vcc, exec, s[80:81]
	s_cbranch_vccz .Lsu_ld7
	global_load_dwordx4 v[16:19], v[244:245], off
	global_load_dwordx4 v[20:23], v[244:245], off offset:512
	global_load_dwordx4 v[24:27], v[244:245], off offset:1024
	global_load_dwordx4 v[28:31], v[244:245], off offset:1536
.Lsu_ld7:
	s_and_b64 vcc, exec, s[70:71]
	s_cbranch_vccz .Lsu_ld8
	global_load_dwordx4 v[32:35], v[242:243], off
	global_load_dwordx4 v[36:39], v[242:243], off offset:512
	global_load_dwordx4 v[96:99], v[242:243], off offset:1024
	global_load_dwordx4 v[100:103], v[242:243], off offset:1536
.Lsu_ld8:
	s_waitcnt vmcnt(0)
	ds_bpermute_b32 v106, v228, v106
	ds_bpermute_b32 v107, v228, v107
	ds_bpermute_b32 v108, v228, v108
	ds_bpermute_b32 v109, v228, v109
	ds_bpermute_b32 v110, v228, v110
	ds_bpermute_b32 v111, v228, v111
	ds_bpermute_b32 v112, v228, v112
	ds_bpermute_b32 v113, v228, v113
	ds_bpermute_b32 v114, v228, v114
	ds_bpermute_b32 v115, v228, v115
	ds_bpermute_b32 v116, v228, v116
	ds_bpermute_b32 v117, v228, v117
	ds_bpermute_b32 v118, v228, v118
	ds_bpermute_b32 v119, v228, v119
	ds_bpermute_b32 v120, v228, v120
	ds_bpermute_b32 v121, v228, v121
	s_and_b64 vcc, exec, s[28:29]
	s_cbranch_vccz .Lsu_mm0
	ds_bpermute_b32 v122, v228, v122
	ds_bpermute_b32 v123, v228, v123
	ds_bpermute_b32 v124, v228, v124
	ds_bpermute_b32 v125, v228, v125
	ds_bpermute_b32 v126, v228, v126
	ds_bpermute_b32 v127, v228, v127
	ds_bpermute_b32 v128, v228, v128
	ds_bpermute_b32 v129, v228, v129
	ds_bpermute_b32 v130, v228, v130
	ds_bpermute_b32 v131, v228, v131
	ds_bpermute_b32 v132, v228, v132
	ds_bpermute_b32 v133, v228, v133
	ds_bpermute_b32 v134, v228, v134
	ds_bpermute_b32 v135, v228, v135
	ds_bpermute_b32 v136, v228, v136
	ds_bpermute_b32 v137, v228, v137
	s_waitcnt lgkmcnt(0)
	v_mfma_f32_16x16x32_bf16 v[72:75], v[106:109], v[122:125], v[72:75]
	v_mfma_f32_16x16x32_bf16 v[72:75], v[110:113], v[126:129], v[72:75]
	v_mfma_f32_16x16x32_bf16 v[72:75], v[114:117], v[130:133], v[72:75]
	v_mfma_f32_16x16x32_bf16 v[72:75], v[118:121], v[134:137], v[72:75]
.Lsu_mm0:
	s_and_b64 vcc, exec, s[30:31]
	s_cbranch_vccz .Lsu_mm1
	ds_bpermute_b32 v138, v228, v138
	ds_bpermute_b32 v139, v228, v139
	ds_bpermute_b32 v140, v228, v140
	ds_bpermute_b32 v141, v228, v141
	ds_bpermute_b32 v142, v228, v142
	ds_bpermute_b32 v143, v228, v143
	ds_bpermute_b32 v144, v228, v144
	ds_bpermute_b32 v145, v228, v145
	ds_bpermute_b32 v146, v228, v146
	ds_bpermute_b32 v147, v228, v147
	ds_bpermute_b32 v148, v228, v148
	ds_bpermute_b32 v149, v228, v149
	ds_bpermute_b32 v150, v228, v150
	ds_bpermute_b32 v151, v228, v151
	ds_bpermute_b32 v152, v228, v152
	ds_bpermute_b32 v153, v228, v153
	s_waitcnt lgkmcnt(0)
	v_mfma_f32_16x16x32_bf16 v[68:71], v[106:109], v[138:141], v[68:71]
	v_mfma_f32_16x16x32_bf16 v[68:71], v[110:113], v[142:145], v[68:71]
	v_mfma_f32_16x16x32_bf16 v[68:71], v[114:117], v[146:149], v[68:71]
	v_mfma_f32_16x16x32_bf16 v[68:71], v[118:121], v[150:153], v[68:71]
.Lsu_mm1:
	s_and_b64 vcc, exec, s[52:53]
	s_cbranch_vccz .Lsu_mm2
	ds_bpermute_b32 v154, v228, v154
	ds_bpermute_b32 v155, v228, v155
	ds_bpermute_b32 v156, v228, v156
	ds_bpermute_b32 v157, v228, v157
	ds_bpermute_b32 v158, v228, v158
	ds_bpermute_b32 v159, v228, v159
	ds_bpermute_b32 v160, v228, v160
	ds_bpermute_b32 v161, v228, v161
	ds_bpermute_b32 v162, v228, v162
	ds_bpermute_b32 v163, v228, v163
	ds_bpermute_b32 v164, v228, v164
	ds_bpermute_b32 v165, v228, v165
	ds_bpermute_b32 v166, v228, v166
	ds_bpermute_b32 v167, v228, v167
	ds_bpermute_b32 v168, v228, v168
	ds_bpermute_b32 v169, v228, v169
	s_waitcnt lgkmcnt(0)
	v_mfma_f32_16x16x32_bf16 v[64:67], v[106:109], v[154:157], v[64:67]
	v_mfma_f32_16x16x32_bf16 v[64:67], v[110:113], v[158:161], v[64:67]
	v_mfma_f32_16x16x32_bf16 v[64:67], v[114:117], v[162:165], v[64:67]
	v_mfma_f32_16x16x32_bf16 v[64:67], v[118:121], v[166:169], v[64:67]
.Lsu_mm2:
	s_and_b64 vcc, exec, s[56:57]
	s_cbranch_vccz .Lsu_mm3
	ds_bpermute_b32 v170, v228, v170
	ds_bpermute_b32 v171, v228, v171
	ds_bpermute_b32 v172, v228, v172
	ds_bpermute_b32 v173, v228, v173
	ds_bpermute_b32 v174, v228, v174
	ds_bpermute_b32 v175, v228, v175
	ds_bpermute_b32 v176, v228, v176
	ds_bpermute_b32 v177, v228, v177
	ds_bpermute_b32 v178, v228, v178
	ds_bpermute_b32 v179, v228, v179
	ds_bpermute_b32 v180, v228, v180
	ds_bpermute_b32 v181, v228, v181
	ds_bpermute_b32 v182, v228, v182
	ds_bpermute_b32 v183, v228, v183
	ds_bpermute_b32 v184, v228, v184
	ds_bpermute_b32 v185, v228, v185
	s_waitcnt lgkmcnt(0)
	v_mfma_f32_16x16x32_bf16 v[60:63], v[106:109], v[170:173], v[60:63]
	v_mfma_f32_16x16x32_bf16 v[60:63], v[110:113], v[174:177], v[60:63]
	v_mfma_f32_16x16x32_bf16 v[60:63], v[114:117], v[178:181], v[60:63]
	v_mfma_f32_16x16x32_bf16 v[60:63], v[118:121], v[182:185], v[60:63]
.Lsu_mm3:
	s_and_b64 vcc, exec, s[66:67]
	s_cbranch_vccz .Lsu_mm4
	ds_bpermute_b32 v186, v228, v186
	ds_bpermute_b32 v187, v228, v187
	ds_bpermute_b32 v188, v228, v188
	ds_bpermute_b32 v189, v228, v189
	ds_bpermute_b32 v190, v228, v190
	ds_bpermute_b32 v191, v228, v191
	ds_bpermute_b32 v192, v228, v192
	ds_bpermute_b32 v193, v228, v193
	ds_bpermute_b32 v194, v228, v194
	ds_bpermute_b32 v195, v228, v195
	ds_bpermute_b32 v196, v228, v196
	ds_bpermute_b32 v197, v228, v197
	ds_bpermute_b32 v198, v228, v198
	ds_bpermute_b32 v199, v228, v199
	ds_bpermute_b32 v200, v228, v200
	ds_bpermute_b32 v201, v228, v201
	s_waitcnt lgkmcnt(0)
	v_mfma_f32_16x16x32_bf16 v[56:59], v[106:109], v[186:189], v[56:59]
	v_mfma_f32_16x16x32_bf16 v[56:59], v[110:113], v[190:193], v[56:59]
	v_mfma_f32_16x16x32_bf16 v[56:59], v[114:117], v[194:197], v[56:59]
	v_mfma_f32_16x16x32_bf16 v[56:59], v[118:121], v[198:201], v[56:59]
.Lsu_mm4:
	s_and_b64 vcc, exec, s[76:77]
	s_cbranch_vccz .Lsu_mm5
	ds_bpermute_b32 v202, v228, v202
	ds_bpermute_b32 v203, v228, v203
	ds_bpermute_b32 v204, v228, v204
	ds_bpermute_b32 v205, v228, v205
	ds_bpermute_b32 v206, v228, v206
	ds_bpermute_b32 v207, v228, v207
	ds_bpermute_b32 v208, v228, v208
	ds_bpermute_b32 v209, v228, v209
	ds_bpermute_b32 v210, v228, v210
	ds_bpermute_b32 v211, v228, v211
	ds_bpermute_b32 v212, v228, v212
	ds_bpermute_b32 v213, v228, v213
	ds_bpermute_b32 v214, v228, v214
	ds_bpermute_b32 v215, v228, v215
	ds_bpermute_b32 v216, v228, v216
	ds_bpermute_b32 v217, v228, v217
	s_waitcnt lgkmcnt(0)
	v_mfma_f32_16x16x32_bf16 v[52:55], v[106:109], v[202:205], v[52:55]
	v_mfma_f32_16x16x32_bf16 v[52:55], v[110:113], v[206:209], v[52:55]
	v_mfma_f32_16x16x32_bf16 v[52:55], v[114:117], v[210:213], v[52:55]
	v_mfma_f32_16x16x32_bf16 v[52:55], v[118:121], v[214:217], v[52:55]
.Lsu_mm5:
	s_and_b64 vcc, exec, s[78:79]
	s_cbranch_vccz .Lsu_mm6
	ds_bpermute_b32 v218, v228, v218
	ds_bpermute_b32 v219, v228, v219
	ds_bpermute_b32 v220, v228, v220
	ds_bpermute_b32 v221, v228, v221
	ds_bpermute_b32 v4, v228, v4
	ds_bpermute_b32 v5, v228, v5
	ds_bpermute_b32 v6, v228, v6
	ds_bpermute_b32 v7, v228, v7
	ds_bpermute_b32 v8, v228, v8
	ds_bpermute_b32 v9, v228, v9
	ds_bpermute_b32 v10, v228, v10
	ds_bpermute_b32 v11, v228, v11
	ds_bpermute_b32 v12, v228, v12
	ds_bpermute_b32 v13, v228, v13
	ds_bpermute_b32 v14, v228, v14
	ds_bpermute_b32 v15, v228, v15
	s_waitcnt lgkmcnt(0)
	v_mfma_f32_16x16x32_bf16 v[48:51], v[106:109], v[218:221], v[48:51]
	v_mfma_f32_16x16x32_bf16 v[48:51], v[110:113], v[4:7], v[48:51]
	v_mfma_f32_16x16x32_bf16 v[48:51], v[114:117], v[8:11], v[48:51]
	v_mfma_f32_16x16x32_bf16 v[48:51], v[118:121], v[12:15], v[48:51]
.Lsu_mm6:
	s_and_b64 vcc, exec, s[80:81]
	s_cbranch_vccz .Lsu_mm7
	ds_bpermute_b32 v16, v228, v16
	ds_bpermute_b32 v17, v228, v17
	ds_bpermute_b32 v18, v228, v18
	ds_bpermute_b32 v19, v228, v19
	ds_bpermute_b32 v20, v228, v20
	ds_bpermute_b32 v21, v228, v21
	ds_bpermute_b32 v22, v228, v22
	ds_bpermute_b32 v23, v228, v23
	ds_bpermute_b32 v24, v228, v24
	ds_bpermute_b32 v25, v228, v25
	ds_bpermute_b32 v26, v228, v26
	ds_bpermute_b32 v27, v228, v27
	ds_bpermute_b32 v28, v228, v28
	ds_bpermute_b32 v29, v228, v29
	ds_bpermute_b32 v30, v228, v30
	ds_bpermute_b32 v31, v228, v31
	s_waitcnt lgkmcnt(0)
	v_mfma_f32_16x16x32_bf16 v[44:47], v[106:109], v[16:19], v[44:47]
	v_mfma_f32_16x16x32_bf16 v[44:47], v[110:113], v[20:23], v[44:47]
	v_mfma_f32_16x16x32_bf16 v[44:47], v[114:117], v[24:27], v[44:47]
	v_mfma_f32_16x16x32_bf16 v[44:47], v[118:121], v[28:31], v[44:47]
.Lsu_mm7:
	s_and_b64 vcc, exec, s[70:71]
	s_cbranch_vccz .Lsu_mm8
	ds_bpermute_b32 v32, v228, v32
	ds_bpermute_b32 v33, v228, v33
	ds_bpermute_b32 v34, v228, v34
	ds_bpermute_b32 v35, v228, v35
	ds_bpermute_b32 v36, v228, v36
	ds_bpermute_b32 v37, v228, v37
	ds_bpermute_b32 v38, v228, v38
	ds_bpermute_b32 v39, v228, v39
	ds_bpermute_b32 v96, v228, v96
	ds_bpermute_b32 v97, v228, v97
	ds_bpermute_b32 v98, v228, v98
	ds_bpermute_b32 v99, v228, v99
	ds_bpermute_b32 v100, v228, v100
	ds_bpermute_b32 v101, v228, v101
	ds_bpermute_b32 v102, v228, v102
	ds_bpermute_b32 v103, v228, v103
	s_waitcnt lgkmcnt(0)
	v_mfma_f32_16x16x32_bf16 v[40:43], v[106:109], v[32:35], v[40:43]
	v_mfma_f32_16x16x32_bf16 v[40:43], v[110:113], v[36:39], v[40:43]
	v_mfma_f32_16x16x32_bf16 v[40:43], v[114:117], v[96:99], v[40:43]
	v_mfma_f32_16x16x32_bf16 v[40:43], v[118:121], v[100:103], v[40:43]
.Lsu_mm8:
	s_branch .LBB0_2303
.LBB0_2302:
	v_mov_b32_e32 v74, v75
	v_mov_b32_e32 v73, v75
	v_mov_b32_e32 v72, v75
	v_mov_b32_e32 v71, v75
	v_mov_b32_e32 v70, v75
	v_mov_b32_e32 v69, v75
	v_mov_b32_e32 v68, v75
	v_mov_b32_e32 v67, v75
	v_mov_b32_e32 v66, v75
	v_mov_b32_e32 v65, v75
	v_mov_b32_e32 v64, v75
	v_mov_b32_e32 v63, v75
	v_mov_b32_e32 v62, v75
	v_mov_b32_e32 v61, v75
	v_mov_b32_e32 v60, v75
	v_mov_b32_e32 v59, v75
	v_mov_b32_e32 v58, v75
	v_mov_b32_e32 v57, v75
	v_mov_b32_e32 v56, v75
	v_mov_b32_e32 v55, v75
	v_mov_b32_e32 v54, v75
	v_mov_b32_e32 v53, v75
	v_mov_b32_e32 v52, v75
	v_mov_b32_e32 v51, v75
	v_mov_b32_e32 v50, v75
	v_mov_b32_e32 v49, v75
	v_mov_b32_e32 v48, v75
	v_mov_b32_e32 v47, v75
	v_mov_b32_e32 v46, v75
	v_mov_b32_e32 v45, v75
	v_mov_b32_e32 v44, v75
	v_mov_b32_e32 v43, v75
	v_mov_b32_e32 v42, v75
	v_mov_b32_e32 v41, v75
	v_mov_b32_e32 v40, v75
